# v33 + GEMM accumulator zeroing with 64-bit moves (64 instead of 128 VALU ops per unit)
# speedup vs baseline: 1.0125x; 1.0117x over previous
.LBB0_306:
	s_ashr_i32 s51, s50, 31
	s_lshl_b64 s[12:13], s[50:51], 19
	s_add_u32 s52, s8, s12
	s_addc_u32 s53, s9, s13
	s_and_b64 s[12:13], s[38:39], exec
	s_cselect_b32 s73, s53, s57
	s_cselect_b32 s74, s52, s56
	s_ashr_i32 s49, s48, 31
	s_lshl_b64 s[12:13], s[48:49], 19
	s_add_u32 s54, s2, s12
	s_addc_u32 s55, s16, s13
	s_and_b64 s[12:13], s[38:39], exec
	s_cselect_b32 s75, s55, s59
	s_cselect_b32 s76, s54, s58
	s_lshl_b64 s[12:13], s[50:51], 11
	v_lshl_add_u64 v[50:51], v[166:167], 0, s[12:13]
	s_lshl_b32 s12, s71, 12
	s_and_b32 s51, s12, 0x1000
	s_lshl_b64 s[12:13], s[48:49], 10
	s_add_u32 s56, s56, 0x40080
	s_addc_u32 s57, s57, 0
	v_lshl_add_u64 v[52:53], v[168:169], 0, s[12:13]
	s_add_u32 s12, s58, 0x100
	s_addc_u32 s13, s59, 0
	v_mov_b64_e32 v[2:3], 0
	v_mov_b64_e32 v[4:5], 0
	v_mov_b64_e32 v[6:7], 0
	v_mov_b64_e32 v[8:9], 0
	v_mov_b64_e32 v[10:11], 0
	v_mov_b64_e32 v[12:13], 0
	v_mov_b64_e32 v[14:15], 0
	v_mov_b64_e32 v[16:17], 0
	v_mov_b64_e32 v[18:19], 0
	v_mov_b64_e32 v[20:21], 0
	v_mov_b64_e32 v[22:23], 0
	v_mov_b64_e32 v[24:25], 0
	v_mov_b64_e32 v[26:27], 0
	v_mov_b64_e32 v[28:29], 0
	v_mov_b64_e32 v[30:31], 0
	v_mov_b64_e32 v[32:33], 0
	v_mov_b64_e32 v[34:35], 0
	v_mov_b64_e32 v[36:37], 0
	v_mov_b64_e32 v[38:39], 0
	v_mov_b64_e32 v[40:41], 0
	v_mov_b64_e32 v[42:43], 0
	v_mov_b64_e32 v[44:45], 0
	v_mov_b64_e32 v[46:47], 0
	v_mov_b64_e32 v[48:49], 0
	v_mov_b64_e32 v[58:59], 0
	v_mov_b64_e32 v[60:61], 0
	v_mov_b64_e32 v[62:63], 0
	v_mov_b64_e32 v[64:65], 0
	v_mov_b64_e32 v[74:75], 0
	v_mov_b64_e32 v[76:77], 0
	v_mov_b64_e32 v[78:79], 0
	v_mov_b64_e32 v[80:81], 0
	v_mov_b64_e32 v[82:83], 0
	v_mov_b64_e32 v[84:85], 0
	v_mov_b64_e32 v[86:87], 0
	v_mov_b64_e32 v[88:89], 0
	v_mov_b64_e32 v[90:91], 0
	v_mov_b64_e32 v[92:93], 0
	v_mov_b64_e32 v[94:95], 0
	v_mov_b64_e32 v[96:97], 0
	v_mov_b64_e32 v[98:99], 0
	v_mov_b64_e32 v[100:101], 0
	v_mov_b64_e32 v[102:103], 0
	v_mov_b64_e32 v[104:105], 0
	v_mov_b64_e32 v[106:107], 0
	v_mov_b64_e32 v[108:109], 0
	v_mov_b64_e32 v[110:111], 0
	v_mov_b64_e32 v[112:113], 0
	v_mov_b64_e32 v[114:115], 0
	v_mov_b64_e32 v[116:117], 0
	v_mov_b64_e32 v[118:119], 0
	v_mov_b64_e32 v[120:121], 0
	v_mov_b64_e32 v[122:123], 0
	v_mov_b64_e32 v[124:125], 0
	v_mov_b64_e32 v[126:127], 0
	v_mov_b64_e32 v[128:129], 0
	v_mov_b64_e32 v[130:131], 0
	v_mov_b64_e32 v[132:133], 0
	v_mov_b64_e32 v[134:135], 0
	v_mov_b64_e32 v[136:137], 0
	v_mov_b64_e32 v[138:139], 0
	v_mov_b64_e32 v[140:141], 0
	v_mov_b64_e32 v[142:143], 0
	v_mov_b64_e32 v[144:145], 0
	s_add_i32 s51, s23, s51
	s_mov_b32 s49, -2
	s_add_i32 s77, s51, 0x800
	s_branch .LBB0_308

.LBB0_387:
	s_ashr_i32 s65, s64, 31
	s_lshl_b64 s[12:13], s[64:65], 11
	v_lshl_add_u64 v[130:131], v[174:175], 0, s[12:13]
	s_lshl_b32 s12, s57, 12
	s_add_i32 s69, s90, -2
	s_and_b32 s65, s12, 0x1000
	s_lshl_b64 s[12:13], s[66:67], 10
	s_add_u32 s74, s74, 0x80
	s_addc_u32 s75, s75, 0
	s_add_u32 s67, s76, 0x100
	v_mov_b64_e32 v[2:3], 0
	v_mov_b64_e32 v[4:5], 0
	v_mov_b64_e32 v[6:7], 0
	v_mov_b64_e32 v[8:9], 0
	v_mov_b64_e32 v[10:11], 0
	v_mov_b64_e32 v[12:13], 0
	v_mov_b64_e32 v[14:15], 0
	v_mov_b64_e32 v[16:17], 0
	v_mov_b64_e32 v[18:19], 0
	v_mov_b64_e32 v[20:21], 0
	v_mov_b64_e32 v[22:23], 0
	v_mov_b64_e32 v[24:25], 0
	v_mov_b64_e32 v[26:27], 0
	v_mov_b64_e32 v[28:29], 0
	v_mov_b64_e32 v[30:31], 0
	v_mov_b64_e32 v[32:33], 0
	v_mov_b64_e32 v[34:35], 0
	v_mov_b64_e32 v[36:37], 0
	v_mov_b64_e32 v[38:39], 0
	v_mov_b64_e32 v[40:41], 0
	v_mov_b64_e32 v[42:43], 0
	v_mov_b64_e32 v[44:45], 0
	v_mov_b64_e32 v[46:47], 0
	v_mov_b64_e32 v[48:49], 0
	v_mov_b64_e32 v[50:51], 0
	v_mov_b64_e32 v[52:53], 0
	v_mov_b64_e32 v[54:55], 0
	v_mov_b64_e32 v[56:57], 0
	v_mov_b64_e32 v[58:59], 0
	v_mov_b64_e32 v[60:61], 0
	v_mov_b64_e32 v[62:63], 0
	v_mov_b64_e32 v[64:65], 0
	v_mov_b64_e32 v[66:67], 0
	v_mov_b64_e32 v[68:69], 0
	v_mov_b64_e32 v[70:71], 0
	v_mov_b64_e32 v[72:73], 0
	v_mov_b64_e32 v[74:75], 0
	v_mov_b64_e32 v[76:77], 0
	v_mov_b64_e32 v[78:79], 0
	v_mov_b64_e32 v[80:81], 0
	v_mov_b64_e32 v[82:83], 0
	v_mov_b64_e32 v[84:85], 0
	v_mov_b64_e32 v[86:87], 0
	v_mov_b64_e32 v[88:89], 0
	v_mov_b64_e32 v[90:91], 0
	v_mov_b64_e32 v[92:93], 0
	v_mov_b64_e32 v[94:95], 0
	v_mov_b64_e32 v[96:97], 0
	v_mov_b64_e32 v[98:99], 0
	v_mov_b64_e32 v[100:101], 0
	v_mov_b64_e32 v[102:103], 0
	v_mov_b64_e32 v[104:105], 0
	v_mov_b64_e32 v[106:107], 0
	v_mov_b64_e32 v[108:109], 0
	v_mov_b64_e32 v[110:111], 0
	v_mov_b64_e32 v[112:113], 0
	v_mov_b64_e32 v[114:115], 0
	v_mov_b64_e32 v[116:117], 0
	v_mov_b64_e32 v[118:119], 0
	v_mov_b64_e32 v[120:121], 0
	v_mov_b64_e32 v[122:123], 0
	v_mov_b64_e32 v[124:125], 0
	v_mov_b64_e32 v[126:127], 0
	v_mov_b64_e32 v[128:129], 0
	s_waitcnt lgkmcnt(0)
	v_lshl_add_u64 v[132:133], v[176:177], 0, s[12:13]
	s_addc_u32 s73, s77, 0
	s_mov_b32 s12, 0
	s_branch .LBB0_389

.LBB0_871:
	s_ashr_i32 s55, s54, 31
	s_lshl_b64 s[12:13], s[54:55], 19
	s_add_u32 s56, s8, s12
	s_addc_u32 s57, s9, s13
	s_and_b64 s[12:13], exec, s[42:43]
	s_cselect_b32 s7, s63, s57
	s_cselect_b32 s45, s62, s56
	s_ashr_i32 s53, s52, 31
	s_lshl_b64 s[12:13], s[52:53], 19
	s_add_u32 s58, s24, s12
	s_addc_u32 s59, s25, s13
	s_and_b64 s[12:13], exec, s[42:43]
	s_cselect_b32 s61, s65, s59
	s_cselect_b32 s75, s64, s58
	s_lshl_b64 s[12:13], s[54:55], 11
	v_lshl_add_u64 v[130:131], v[164:165], 0, s[12:13]
	s_lshl_b32 s12, s74, 12
	s_and_b32 s55, s12, 0x1000
	s_lshl_b64 s[12:13], s[52:53], 10
	v_lshl_add_u64 v[132:133], v[166:167], 0, s[12:13]
	v_readlane_b32 s12, v253, 43
	v_readlane_b32 s13, v253, 44
	s_or_b64 s[42:43], s[42:43], s[12:13]
	s_add_u32 s62, s62, 0x40080
	s_addc_u32 s63, s63, 0
	s_add_u32 s12, s64, 0x100
	v_mov_b64_e32 v[2:3], 0
	v_mov_b64_e32 v[4:5], 0
	v_mov_b64_e32 v[6:7], 0
	v_mov_b64_e32 v[8:9], 0
	v_mov_b64_e32 v[10:11], 0
	v_mov_b64_e32 v[12:13], 0
	v_mov_b64_e32 v[14:15], 0
	v_mov_b64_e32 v[16:17], 0
	v_mov_b64_e32 v[18:19], 0
	v_mov_b64_e32 v[20:21], 0
	v_mov_b64_e32 v[22:23], 0
	v_mov_b64_e32 v[24:25], 0
	v_mov_b64_e32 v[26:27], 0
	v_mov_b64_e32 v[28:29], 0
	v_mov_b64_e32 v[30:31], 0
	v_mov_b64_e32 v[32:33], 0
	v_mov_b64_e32 v[34:35], 0
	v_mov_b64_e32 v[36:37], 0
	v_mov_b64_e32 v[38:39], 0
	v_mov_b64_e32 v[40:41], 0
	v_mov_b64_e32 v[42:43], 0
	v_mov_b64_e32 v[44:45], 0
	v_mov_b64_e32 v[46:47], 0
	v_mov_b64_e32 v[48:49], 0
	v_mov_b64_e32 v[50:51], 0
	v_mov_b64_e32 v[52:53], 0
	v_mov_b64_e32 v[54:55], 0
	v_mov_b64_e32 v[56:57], 0
	v_mov_b64_e32 v[58:59], 0
	v_mov_b64_e32 v[60:61], 0
	v_mov_b64_e32 v[62:63], 0
	v_mov_b64_e32 v[64:65], 0
	v_mov_b64_e32 v[66:67], 0
	v_mov_b64_e32 v[68:69], 0
	v_mov_b64_e32 v[70:71], 0
	v_mov_b64_e32 v[72:73], 0
	v_mov_b64_e32 v[74:75], 0
	v_mov_b64_e32 v[76:77], 0
	v_mov_b64_e32 v[78:79], 0
	v_mov_b64_e32 v[80:81], 0
	v_mov_b64_e32 v[82:83], 0
	v_mov_b64_e32 v[84:85], 0
	v_mov_b64_e32 v[86:87], 0
	v_mov_b64_e32 v[88:89], 0
	v_mov_b64_e32 v[90:91], 0
	v_mov_b64_e32 v[92:93], 0
	v_mov_b64_e32 v[94:95], 0
	v_mov_b64_e32 v[96:97], 0
	v_mov_b64_e32 v[98:99], 0
	v_mov_b64_e32 v[100:101], 0
	v_mov_b64_e32 v[102:103], 0
	v_mov_b64_e32 v[104:105], 0
	v_mov_b64_e32 v[106:107], 0
	v_mov_b64_e32 v[108:109], 0
	v_mov_b64_e32 v[110:111], 0
	v_mov_b64_e32 v[112:113], 0
	v_mov_b64_e32 v[114:115], 0
	v_mov_b64_e32 v[116:117], 0
	v_mov_b64_e32 v[118:119], 0
	v_mov_b64_e32 v[120:121], 0
	v_mov_b64_e32 v[122:123], 0
	v_mov_b64_e32 v[124:125], 0
	v_mov_b64_e32 v[126:127], 0
	v_mov_b64_e32 v[128:129], 0
	s_addc_u32 s13, s65, 0
	s_mov_b32 s53, -2
	s_add_i32 s55, s73, s55
	s_branch .LBB0_873
